# latent diff-attention: first V-fragment tr-reads of a tile issued in the MFMA->VALU hazard shadow after QK^T (ahead of the softmax-max/branch chain); max temps renamed
# baseline (speedup 1.0000x reference)
; __device__ __forceinline__ float max3f_(float a, float b, float c) { float r; asm("v_max3_f32 %0, %1, %2, %3" : "=v"(r) : "v"(a), "v"(b), "v"(c)); return r; }
; template <int KW, int DV, bool NA> ...
;     ...
;     auto tile = [&](int i, const unsigned char* Kt, const unsigned char* Vt) {
;         constexpr int DT = DV / 32;
;         f32x16 p0, p1;
; #pragma unroll
;         for (int d0 = 0; d0 < 4; ++d0) {
;             const bf16x8 a0 = *(const bf16x8*)(Kt + q32 * KSTR + (kcoff + 16 * d0 + 8 * hi) * 2);
;             const bf16x8 a1 = *(const bf16x8*)(Kt + (32 + q32) * KSTR + (kcoff + 16 * d0 + 8 * hi) * 2);
;             if (d0 == 0) { p0 = __builtin_amdgcn_mfma_f32_32x32x16_bf16(a0, qf[0], negm, 0, 0, 0); p1 = __builtin_amdgcn_mfma_f32_32x32x16_bf16(a1, qf[0], negm, 0, 0, 0); }
;             else { p0 = __builtin_amdgcn_mfma_f32_32x32x16_bf16(a0, qf[d0], p0, 0, 0, 0); p1 = __builtin_amdgcn_mfma_f32_32x32x16_bf16(a1, qf[d0], p1, 0, 0, 0); }
;         }
;         if (NA && i < n1) {
;             const int kr = na_row0 + i, dr = kr - na_r + 7;
;             const int cs = min(max(na_c - 8, 0), 48);
;             const float* rb = rpbs + dr * 31 - na_c + 15;
; #pragma unroll
;             for (int r = 0; r < 16; ++r) {
;                 const int kc0 = (r & 3) + 8 * (r >> 2) + 4 * hi, kc1 = kc0 + 32;
;                 const bool ok0 = (kc0 >= cs) && (kc0 < cs + 16), ok1 = (kc1 >= cs) && (kc1 < cs + 16);
;                 p0[r] = ok0 ? p0[r] + rb[kc0] : -1e30f;
;                 p1[r] = ok1 ? p1[r] + rb[kc1] : -1e30f;
;             }
;         }
;         asm volatile("s_nop 15\n\ts_nop 7" : "+v"(p0), "+v"(p1));
;         float mxa = max3f_(p0[0], p0[1], p1[0]), mxb = max3f_(p0[2], p0[3], p1[1]);
;         mxa = max3f_(mxa, p1[2], p1[3]);
; #pragma unroll
;         for (int r = 4; r < 16; r += 4) { mxa = max3f_(mxa, p0[r], p0[r + 1]); mxb = max3f_(mxb, p0[r + 2], p0[r + 3]); mxa = max3f_(mxa, p1[r], p1[r + 1]); mxb = max3f_(mxb, p1[r + 2], p1[r + 3]); }
;         float mx = max3f_(mxa, mxb, mxb);
;         mx = xor32_max(mx);
;         if (first || __any(mx > 6.f)) {
;     ...
;         const unsigned vb = (unsigned)(uintptr_t)(Vt + (4 * hi + ((lane & 15) >> 2)) * VSTR + (16 * ((lane >> 4) & 1) + 4 * (lane & 3)) * 2);
;         s16x4 lo[DT], hh[DT];
;     ...
; #pragma unroll
;         for (int d = 0; d < DT; ++d) TR_ISSUE(0, d);
.LBB0_593:
	s_mul_i32 s2, s9, 0x9400
	s_add_i32 s2, s2, 0
	v_add3_u32 v204, s2, v193, v194
	ds_read_b128 v[82:85], v204
	ds_read_b128 v[198:201], v204 offset:8704
	s_xor_b64 s[4:5], s[0:1], -1
	s_and_b64 vcc, exec, s[4:5]
	s_waitcnt lgkmcnt(1)
	v_mfma_f32_32x32x16_bf16 v[98:113], v[82:85], v[114:117], v[66:81]
	s_waitcnt lgkmcnt(0)
	v_mfma_f32_32x32x16_bf16 v[82:97], v[198:201], v[114:117], v[66:81]
	ds_read_b128 v[198:201], v204 offset:32
	s_waitcnt lgkmcnt(0)
	v_mfma_f32_32x32x16_bf16 v[98:113], v[198:201], v[118:121], v[98:113]
	ds_read_b128 v[198:201], v204 offset:8736
	s_waitcnt lgkmcnt(0)
	v_mfma_f32_32x32x16_bf16 v[82:97], v[198:201], v[118:121], v[82:97]
	ds_read_b128 v[198:201], v204 offset:64
	s_waitcnt lgkmcnt(0)
	v_mfma_f32_32x32x16_bf16 v[98:113], v[198:201], v[122:125], v[98:113]
	ds_read_b128 v[198:201], v204 offset:8768
	s_waitcnt lgkmcnt(0)
	v_mfma_f32_32x32x16_bf16 v[82:97], v[198:201], v[122:125], v[82:97]
	ds_read_b128 v[198:201], v204 offset:96
	s_waitcnt lgkmcnt(0)
	v_mfma_f32_32x32x16_bf16 v[98:113], v[198:201], v[126:129], v[98:113]
	ds_read_b128 v[198:201], v204 offset:8800
	s_waitcnt lgkmcnt(0)
	v_mfma_f32_32x32x16_bf16 v[82:97], v[198:201], v[126:129], v[82:97]
	v_add_u32_e32 v198, s2, v195
	v_add3_u32 v204, v198, v0, s90
	ds_read_b64_tr_b16 v[198:199], v204 offset:0
	ds_read_b64_tr_b16 v[200:201], v204 offset:2560
	ds_read_b64_tr_b16 v[206:207], v204 offset:64
	ds_read_b64_tr_b16 v[208:209], v204 offset:2624
	ds_read_b64_tr_b16 v[210:211], v204 offset:128
	ds_read_b64_tr_b16 v[212:213], v204 offset:2688
	ds_read_b64_tr_b16 v[214:215], v204 offset:192
	ds_read_b64_tr_b16 v[216:217], v204 offset:2752
	s_nop 1
	v_max3_f32 v218, v98, v99, v82
	v_max3_f32 v219, v100, v101, v83
	v_max3_f32 v218, v218, v84, v85
	v_max3_f32 v219, v219, v104, v105
	v_max3_f32 v218, v218, v102, v103
	v_max3_f32 v219, v219, v88, v89
	v_max3_f32 v218, v218, v86, v87
	v_max3_f32 v219, v219, v108, v109
	v_max3_f32 v218, v218, v106, v107
	v_max3_f32 v219, v219, v92, v93
	v_max3_f32 v218, v218, v90, v91
	v_max3_f32 v219, v219, v112, v113
	v_max3_f32 v218, v218, v110, v111
	v_max3_f32 v219, v219, v96, v97
	v_max3_f32 v218, v218, v94, v95
	v_max3_f32 v218, v218, v219, v219
	v_mov_b32_e32 v219, v218
	s_nop 1
	v_permlane32_swap_b32_e32 v218, v219
	v_max_f32_e32 v219, v219, v219
	v_max_f32_e32 v218, v218, v218
	v_max_f32_e32 v218, v218, v219
	s_cbranch_vccz .LBB0_595
	v_cmp_lt_f32_e32 vcc, s80, v218
	s_cmp_lg_u64 vcc, 0
	s_cselect_b64 s[4:5], -1, 0
	s_cbranch_execz .LBB0_596
	s_branch .LBB0_597

; #define TR_ISSUE(KS, d) do { \
;             asm volatile("ds_read_b64_tr_b16 %0, %1 offset:%c2" : "=&v"(lo[d]) : "v"(vb), "i"((16 * (KS)) * VSTR + 64 * (d)) : "memory"); \
;             asm volatile("ds_read_b64_tr_b16 %0, %1 offset:%c2" : "=&v"(hh[d]) : "v"(vb), "i"((16 * (KS) + 8) * VSTR + 64 * (d)) : "memory"); } while (0)
; #define LGKM_WAIT(N) do { if constexpr ((N) == 6) asm volatile("s_waitcnt lgkmcnt(6)" ::: "memory"); else if constexpr ((N) == 4) asm volatile("s_waitcnt lgkmcnt(4)" ::: "memory"); \
;             else if constexpr ((N) == 2) asm volatile("s_waitcnt lgkmcnt(2)" ::: "memory"); else asm volatile("s_waitcnt lgkmcnt(0)" ::: "memory"); __builtin_amdgcn_sched_barrier(0); } while (0)
; #define SM_SLICE(P, LO, HI) _Pragma("unroll") for (int r = (LO); r < (HI); ++r) { P[r] = __builtin_amdgcn_exp2f(P[r]); ps += P[r]; }
; #define PACK8(P, B) ((u32x4){pk2(P[(B)], P[(B) + 1]), pk2(P[(B) + 2], P[(B) + 3]), pk2(P[(B) + 4], P[(B) + 5]), pk2(P[(B) + 6], P[(B) + 7])})
; template <int KW, int DV, bool NA> ...
;     ...
;         if (first || __any(mx > 6.f)) {
;             const float dl = first ? mx : fmaxf(mx, 0.f);
;             const float f = first ? 0.f : __builtin_amdgcn_exp2f(-dl);
;             m_ref += dl; l_run *= f;
; #pragma unroll
;             for (int r = 0; r < 16; ++r) negm[r] = -m_ref;
;             asm volatile("" : "+v"(negm));
; #pragma unroll
;             for (int r = 0; r < 16; ++r) { p0[r] -= dl; p1[r] -= dl; }
; #pragma unroll
;             for (int d = 0; d < DT; ++d)
; #pragma unroll
;                 for (int r = 0; r < 16; ++r) o[d][r] *= f;
;             first = false;
;         }
;         const unsigned vb = (unsigned)(uintptr_t)(Vt + (4 * hi + ((lane & 15) >> 2)) * VSTR + (16 * ((lane >> 4) & 1) + 4 * (lane & 3)) * 2);
;         s16x4 lo[DT], hh[DT];
;     ...
; #pragma unroll
;         for (int d = 0; d < DT; ++d) TR_ISSUE(0, d);
;         float ps = 0.f;
;         SM_SLICE(p0, 0, 8); pw[0] = PACK8(p0, 0);
; #pragma unroll
;         for (int d = 0; d < DT; ++d) {
;             LGKM_WAIT(2 * (DT - 1));
;             o[d] = __builtin_amdgcn_mfma_f32_32x32x16_bf16(PV_VF(d), __builtin_bit_cast(bf16x8, pw[0]), o[d], 0, 0, 0);
;             TR_ISSUE(1, d);
;             SM_SLICE(p0, 8 + d * (8 / DT), 8 + (d + 1) * (8 / DT));
.LBB0_597:
	s_andn2_b64 vcc, exec, s[4:5]
	s_cbranch_vccnz .LBB0_599
	v_max_f32_e32 v66, v218, v218
	v_max_f32_e32 v66, 0, v66
	v_cndmask_b32_e64 v218, v66, v218, s[0:1]
	v_exp_f32_e64 v68, -v218
	v_add_f32_e32 v196, v196, v218
	v_xor_b32_e32 v66, 0x80000000, v196
	v_mov_b32_e32 v67, v66
	v_cndmask_b32_e64 v220, v68, 0, s[0:1]
	v_mul_f32_e32 v197, v197, v220
	v_mov_b32_e32 v68, v66
	v_mov_b32_e32 v69, v66
	v_mov_b32_e32 v70, v66
	v_mov_b32_e32 v71, v66
	v_mov_b32_e32 v72, v66
	v_mov_b32_e32 v73, v66
	v_mov_b32_e32 v74, v66
	v_mov_b32_e32 v75, v66
	v_mov_b32_e32 v76, v66
	v_mov_b32_e32 v77, v66
	v_mov_b32_e32 v78, v66
	v_mov_b32_e32 v79, v66
	v_mov_b32_e32 v80, v66
	v_mov_b32_e32 v81, v66
	v_pk_add_f32 v[98:99], v[98:99], v[218:219] op_sel_hi:[1,0] neg_lo:[0,1] neg_hi:[0,1]
	v_pk_add_f32 v[82:83], v[82:83], v[218:219] op_sel_hi:[1,0] neg_lo:[0,1] neg_hi:[0,1]
	v_pk_add_f32 v[100:101], v[100:101], v[218:219] op_sel_hi:[1,0] neg_lo:[0,1] neg_hi:[0,1]
	v_pk_add_f32 v[84:85], v[84:85], v[218:219] op_sel_hi:[1,0] neg_lo:[0,1] neg_hi:[0,1]
	v_pk_add_f32 v[102:103], v[102:103], v[218:219] op_sel_hi:[1,0] neg_lo:[0,1] neg_hi:[0,1]
	v_pk_add_f32 v[86:87], v[86:87], v[218:219] op_sel_hi:[1,0] neg_lo:[0,1] neg_hi:[0,1]
	v_pk_add_f32 v[104:105], v[104:105], v[218:219] op_sel_hi:[1,0] neg_lo:[0,1] neg_hi:[0,1]
	v_pk_add_f32 v[88:89], v[88:89], v[218:219] op_sel_hi:[1,0] neg_lo:[0,1] neg_hi:[0,1]
	v_pk_add_f32 v[106:107], v[106:107], v[218:219] op_sel_hi:[1,0] neg_lo:[0,1] neg_hi:[0,1]
	v_pk_add_f32 v[90:91], v[90:91], v[218:219] op_sel_hi:[1,0] neg_lo:[0,1] neg_hi:[0,1]
	v_pk_add_f32 v[108:109], v[108:109], v[218:219] op_sel_hi:[1,0] neg_lo:[0,1] neg_hi:[0,1]
	v_pk_add_f32 v[92:93], v[92:93], v[218:219] op_sel_hi:[1,0] neg_lo:[0,1] neg_hi:[0,1]
	v_pk_add_f32 v[110:111], v[110:111], v[218:219] op_sel_hi:[1,0] neg_lo:[0,1] neg_hi:[0,1]
	v_pk_add_f32 v[94:95], v[94:95], v[218:219] op_sel_hi:[1,0] neg_lo:[0,1] neg_hi:[0,1]
	v_pk_add_f32 v[112:113], v[112:113], v[218:219] op_sel_hi:[1,0] neg_lo:[0,1] neg_hi:[0,1]
	v_pk_add_f32 v[96:97], v[96:97], v[218:219] op_sel_hi:[1,0] neg_lo:[0,1] neg_hi:[0,1]
	v_pk_mul_f32 v[64:65], v[64:65], v[220:221] op_sel_hi:[1,0]
	v_pk_mul_f32 v[62:63], v[62:63], v[220:221] op_sel_hi:[1,0]
	v_pk_mul_f32 v[60:61], v[60:61], v[220:221] op_sel_hi:[1,0]
	v_pk_mul_f32 v[58:59], v[58:59], v[220:221] op_sel_hi:[1,0]
	v_pk_mul_f32 v[56:57], v[56:57], v[220:221] op_sel_hi:[1,0]
	v_pk_mul_f32 v[54:55], v[54:55], v[220:221] op_sel_hi:[1,0]
	v_pk_mul_f32 v[52:53], v[52:53], v[220:221] op_sel_hi:[1,0]
	v_pk_mul_f32 v[50:51], v[50:51], v[220:221] op_sel_hi:[1,0]
	v_pk_mul_f32 v[48:49], v[48:49], v[220:221] op_sel_hi:[1,0]
	v_pk_mul_f32 v[46:47], v[46:47], v[220:221] op_sel_hi:[1,0]
	v_pk_mul_f32 v[44:45], v[44:45], v[220:221] op_sel_hi:[1,0]
	v_pk_mul_f32 v[42:43], v[42:43], v[220:221] op_sel_hi:[1,0]
	v_pk_mul_f32 v[40:41], v[40:41], v[220:221] op_sel_hi:[1,0]
	v_pk_mul_f32 v[38:39], v[38:39], v[220:221] op_sel_hi:[1,0]
	v_pk_mul_f32 v[36:37], v[36:37], v[220:221] op_sel_hi:[1,0]
	v_pk_mul_f32 v[34:35], v[34:35], v[220:221] op_sel_hi:[1,0]
	v_pk_mul_f32 v[32:33], v[32:33], v[220:221] op_sel_hi:[1,0]
	v_pk_mul_f32 v[30:31], v[30:31], v[220:221] op_sel_hi:[1,0]
	v_pk_mul_f32 v[28:29], v[28:29], v[220:221] op_sel_hi:[1,0]
	v_pk_mul_f32 v[26:27], v[26:27], v[220:221] op_sel_hi:[1,0]
	v_pk_mul_f32 v[24:25], v[24:25], v[220:221] op_sel_hi:[1,0]
	v_pk_mul_f32 v[22:23], v[22:23], v[220:221] op_sel_hi:[1,0]
	v_pk_mul_f32 v[20:21], v[20:21], v[220:221] op_sel_hi:[1,0]
	v_pk_mul_f32 v[18:19], v[18:19], v[220:221] op_sel_hi:[1,0]
	v_pk_mul_f32 v[16:17], v[16:17], v[220:221] op_sel_hi:[1,0]
	v_pk_mul_f32 v[14:15], v[14:15], v[220:221] op_sel_hi:[1,0]
	v_pk_mul_f32 v[12:13], v[12:13], v[220:221] op_sel_hi:[1,0]
	v_pk_mul_f32 v[10:11], v[10:11], v[220:221] op_sel_hi:[1,0]
	v_pk_mul_f32 v[8:9], v[8:9], v[220:221] op_sel_hi:[1,0]
	v_pk_mul_f32 v[6:7], v[6:7], v[220:221] op_sel_hi:[1,0]
	v_pk_mul_f32 v[4:5], v[4:5], v[220:221] op_sel_hi:[1,0]
	v_pk_mul_f32 v[2:3], v[2:3], v[220:221] op_sel_hi:[1,0]
.LBB0_599:
	v_exp_f32_e32 v98, v98
	v_exp_f32_e32 v99, v99
	v_exp_f32_e32 v100, v100
	v_exp_f32_e32 v101, v101
	v_exp_f32_e32 v102, v102
	v_exp_f32_e32 v103, v103
	v_exp_f32_e32 v104, v104
	v_exp_f32_e32 v105, v105
	s_waitcnt lgkmcnt(6)
	v_cvt_pk_bf16_f32 v218, v98, v99
	v_cvt_pk_bf16_f32 v219, v100, v101
	v_cvt_pk_bf16_f32 v220, v102, v103
	v_cvt_pk_bf16_f32 v221, v104, v105
	s_nop 1
	v_mfma_f32_32x32x16_bf16 v[50:65], v[198:201], v[218:221], v[50:65]
	ds_read_b64_tr_b16 v[198:199], v204 offset:5120
	v_exp_f32_e32 v106, v106
	v_exp_f32_e32 v107, v107
	ds_read_b64_tr_b16 v[200:201], v204 offset:7680
	s_waitcnt lgkmcnt(6)
	v_mfma_f32_32x32x16_bf16 v[34:49], v[206:209], v[218:221], v[34:49]
	ds_read_b64_tr_b16 v[206:207], v204 offset:5184
	v_exp_f32_e32 v108, v108
	v_exp_f32_e32 v109, v109
	ds_read_b64_tr_b16 v[208:209], v204 offset:7744
	s_waitcnt lgkmcnt(6)
	v_mfma_f32_32x32x16_bf16 v[18:33], v[210:213], v[218:221], v[18:33]
	ds_read_b64_tr_b16 v[210:211], v204 offset:5248
	v_exp_f32_e32 v110, v110
	v_exp_f32_e32 v111, v111
	ds_read_b64_tr_b16 v[212:213], v204 offset:7808
	s_waitcnt lgkmcnt(6)
	v_mfma_f32_32x32x16_bf16 v[2:17], v[214:217], v[218:221], v[2:17]
	ds_read_b64_tr_b16 v[214:215], v204 offset:5312
	v_exp_f32_e32 v112, v112
	v_exp_f32_e32 v113, v113
	ds_read_b64_tr_b16 v[216:217], v204 offset:7872
	s_waitcnt lgkmcnt(6)
	v_cvt_pk_bf16_f32 v218, v106, v107
	v_cvt_pk_bf16_f32 v219, v108, v109
	v_cvt_pk_bf16_f32 v220, v110, v111
	v_cvt_pk_bf16_f32 v221, v112, v113
	s_nop 1
	v_mfma_f32_32x32x16_bf16 v[50:65], v[198:201], v[218:221], v[50:65]
	ds_read_b64_tr_b16 v[198:199], v204 offset:10240
	v_exp_f32_e32 v82, v82
	v_exp_f32_e32 v83, v83
	ds_read_b64_tr_b16 v[200:201], v204 offset:12800
	s_waitcnt lgkmcnt(6)
; template <int KW, int DV, bool NA> ...
;     ...
;     auto tile = [&](int i, const unsigned char* Kt, const unsigned char* Vt) {
;         constexpr int DT = DV / 32;
;         f32x16 p0, p1;
; #pragma unroll
;         for (int d0 = 0; d0 < 4; ++d0) {
;             const bf16x8 a0 = *(const bf16x8*)(Kt + q32 * KSTR + (kcoff + 16 * d0 + 8 * hi) * 2);
;             const bf16x8 a1 = *(const bf16x8*)(Kt + (32 + q32) * KSTR + (kcoff + 16 * d0 + 8 * hi) * 2);
;     ...
;             __builtin_amdgcn_sched_barrier(0);
;         }
;         pw[1] = PACK8(p0, 8);
; #pragma unroll
;         for (int d = 0; d < DT; ++d) {
;             LGKM_WAIT(2 * (DT - 1));
;             o[d] = __builtin_amdgcn_mfma_f32_32x32x16_bf16(PV_VF(d), __builtin_bit_cast(bf16x8, pw[1]), o[d], 0, 0, 0);
;             TR_ISSUE(2, d);
;             SM_SLICE(p1, d * (8 / DT), (d + 1) * (8 / DT));
;             __builtin_amdgcn_sched_barrier(0);
;         }
;         pw[2] = PACK8(p1, 0);
; #pragma unroll
;         for (int d = 0; d < DT; ++d) {
;             LGKM_WAIT(2 * (DT - 1));
;             o[d] = __builtin_amdgcn_mfma_f32_32x32x16_bf16(PV_VF(d), __builtin_bit_cast(bf16x8, pw[2]), o[d], 0, 0, 0);
;             TR_ISSUE(3, d);
;             SM_SLICE(p1, 8 + d * (8 / DT), 8 + (d + 1) * (8 / DT));
;             __builtin_amdgcn_sched_barrier(0);
;         }
;         pw[3] = PACK8(p1, 8);
;         l_run += ps;
;         asm volatile("s_waitcnt lgkmcnt(0)" ::: "memory"); __builtin_amdgcn_sched_barrier(0);
; #pragma unroll
;         for (int d = 0; d < DT; ++d) o[d] = __builtin_amdgcn_mfma_f32_32x32x16_bf16(PV_VF(d), __builtin_bit_cast(bf16x8, pw[3]), o[d], 0, 0, 0);
;     ...
;     };
;     prefetch(0, kA, vA); stash(0, kA, vA);
;     if (ntile > 1) prefetch(1, kB, vB);
;     if (ntile > 2) prefetch(2, kA, vA);
;     __syncthreads();
;     int st_cur = 0, st_prev = 2, st_next = 1;
;     auto step = [&](int i, u32x4 (&kreg)[NK], u32x4 (&vreg)[NV]) {
;         if (i + 1 < ntile) { stash(st_next, kreg, vreg); if (i + 3 < ntile) prefetch(i + 3, kreg, vreg); }
;         const unsigned char* Kt = lds + st_cur * STAGE;
;         if (is_active(i)) tile(i, Kt, Kt + 64 * KSTR);
;         __syncthreads();
;         const int t_ = st_prev; st_prev = st_cur; st_cur = st_next; st_next = t_;
;     };
; #pragma unroll 1
;     for (int i = 0; i < ntile; i += 2) { step(i, kB, vB); if (i + 1 < ntile) step(i + 1, kA, vA); }
	v_mfma_f32_32x32x16_bf16 v[34:49], v[206:209], v[218:221], v[34:49]
	ds_read_b64_tr_b16 v[206:207], v204 offset:10304
	v_exp_f32_e32 v84, v84
	v_exp_f32_e32 v85, v85
	ds_read_b64_tr_b16 v[208:209], v204 offset:12864
	s_waitcnt lgkmcnt(6)
	v_mfma_f32_32x32x16_bf16 v[18:33], v[210:213], v[218:221], v[18:33]
	ds_read_b64_tr_b16 v[210:211], v204 offset:10368
	v_exp_f32_e32 v86, v86
	v_exp_f32_e32 v87, v87
	ds_read_b64_tr_b16 v[212:213], v204 offset:12928
	s_waitcnt lgkmcnt(6)
	v_mfma_f32_32x32x16_bf16 v[2:17], v[214:217], v[218:221], v[2:17]
	ds_read_b64_tr_b16 v[214:215], v204 offset:10432
	v_exp_f32_e32 v88, v88
	v_exp_f32_e32 v89, v89
	ds_read_b64_tr_b16 v[216:217], v204 offset:12992
	s_waitcnt lgkmcnt(6)
	v_cvt_pk_bf16_f32 v218, v82, v83
	v_cvt_pk_bf16_f32 v219, v84, v85
	v_cvt_pk_bf16_f32 v220, v86, v87
	v_cvt_pk_bf16_f32 v221, v88, v89
	s_nop 1
	v_mfma_f32_32x32x16_bf16 v[50:65], v[198:201], v[218:221], v[50:65]
	ds_read_b64_tr_b16 v[198:199], v204 offset:15360
	ds_read_b64_tr_b16 v[200:201], v204 offset:17920
	s_waitcnt lgkmcnt(6)
	v_mfma_f32_32x32x16_bf16 v[34:49], v[206:209], v[218:221], v[34:49]
	ds_read_b64_tr_b16 v[206:207], v204 offset:15424
	ds_read_b64_tr_b16 v[208:209], v204 offset:17984
	s_waitcnt lgkmcnt(6)
	v_mfma_f32_32x32x16_bf16 v[18:33], v[210:213], v[218:221], v[18:33]
	ds_read_b64_tr_b16 v[210:211], v204 offset:15488
	ds_read_b64_tr_b16 v[212:213], v204 offset:18048
	s_waitcnt lgkmcnt(6)
	v_mfma_f32_32x32x16_bf16 v[2:17], v[214:217], v[218:221], v[2:17]
	ds_read_b64_tr_b16 v[214:215], v204 offset:15552
	v_exp_f32_e32 v90, v90
	v_exp_f32_e32 v91, v91
	v_exp_f32_e32 v92, v92
	v_exp_f32_e32 v93, v93
	v_exp_f32_e32 v94, v94
	v_exp_f32_e32 v95, v95
	v_exp_f32_e32 v96, v96
	v_exp_f32_e32 v97, v97
	ds_read_b64_tr_b16 v[216:217], v204 offset:18112
	s_waitcnt lgkmcnt(0)
	v_cvt_pk_bf16_f32 v218, v90, v91
	v_cvt_pk_bf16_f32 v219, v92, v93
	v_cvt_pk_bf16_f32 v220, v94, v95
	v_cvt_pk_bf16_f32 v221, v96, v97
	s_nop 1
	v_mfma_f32_32x32x16_bf16 v[50:65], v[198:201], v[218:221], v[50:65]
	s_cmpk_gt_u32 s12, 0x41
	s_barrier
	v_mfma_f32_32x32x16_bf16 v[34:49], v[206:209], v[218:221], v[34:49]
	v_mfma_f32_32x32x16_bf16 v[18:33], v[210:213], v[218:221], v[18:33]
	v_mfma_f32_32x32x16_bf16 v[2:17], v[214:217], v[218:221], v[2:17]
	s_cbranch_scc1 .LBB0_602
	s_mul_i32 s0, s11, 0x9400
	s_add_i32 s0, s0, 0
	v_add3_u32 v198, s0, v187, v188
	s_waitcnt vmcnt(0)
	ds_write_b128 v198, v[146:149]
	v_add3_u32 v198, s0, v189, v190
	ds_write_b128 v198, v[150:153]
	v_add3_u32 v198, s0, v191, v188
	ds_write_b128 v198, v[154:157] offset:17408
	v_add3_u32 v198, s0, v192, v190
	s_cmp_gt_u32 s12, 63
	ds_write_b128 v198, v[158:161] offset:17408
	s_cbranch_scc1 .LBB0_602
	s_cmp_lt_u32 s12, 60
	s_cselect_b64 vcc, -1, 0
	s_and_b64 s[0:1], vcc, exec
	s_cselect_b32 s0, 0, 0xffffffc0
	s_add_i32 s2, s0, s8
	v_cndmask_b32_e32 v147, v173, v167, vcc
	v_cndmask_b32_e32 v146, v172, v166, vcc
	s_lshl_b64 s[0:1], s[2:3], 6
	v_lshl_add_u64 v[146:147], s[0:1], 0, v[146:147]
	v_lshl_add_u64 v[154:155], v[146:147], 0, v[168:169]
	v_lshl_add_u64 v[156:157], v[146:147], 0, v[170:171]
	v_mad_u64_u32 v[148:149], s[0:1], v154, s33, v[174:175]
	v_mad_u64_u32 v[150:151], s[0:1], v156, s33, v[176:177]
	v_mad_u64_u32 v[158:159], s[0:1], v154, s33, v[178:179]
	v_mad_u64_u32 v[160:161], s[0:1], v156, s33, v[180:181]
	v_mad_i32_i24 v149, v155, s33, v149
	v_mad_i32_i24 v151, v157, s33, v151
	v_mad_i32_i24 v159, v155, s33, v159
	v_mad_i32_i24 v161, v157, s33, v161
	global_load_dwordx4 v[146:149], v[148:149], off
	s_nop 0
	global_load_dwordx4 v[150:153], v[150:151], off
	s_nop 0
	global_load_dwordx4 v[154:157], v[158:159], off
	s_nop 0
	global_load_dwordx4 v[158:161], v[160:161], off
.LBB0_602:
	v_add_f32_e32 v98, 0, v98
	v_add_f32_e32 v98, v99, v98
	v_add_f32_e32 v98, v100, v98
	v_add_f32_e32 v98, v101, v98
	v_add_f32_e32 v98, v102, v98
	v_add_f32_e32 v98, v103, v98
	v_add_f32_e32 v98, v104, v98
	v_add_f32_e32 v98, v105, v98
	v_add_f32_e32 v98, v106, v98
	v_add_f32_e32 v98, v107, v98
	v_add_f32_e32 v98, v108, v98
	v_add_f32_e32 v98, v109, v98
	v_add_f32_e32 v98, v110, v98
	v_add_f32_e32 v98, v111, v98
	v_add_f32_e32 v98, v112, v98
	v_add_f32_e32 v98, v113, v98
	v_add_f32_e32 v82, v82, v98
	v_add_f32_e32 v82, v83, v82
	v_add_f32_e32 v82, v84, v82
	v_add_f32_e32 v82, v85, v82
	v_add_f32_e32 v82, v86, v82
	v_add_f32_e32 v82, v87, v82
	v_add_f32_e32 v82, v88, v82
	v_add_f32_e32 v82, v89, v82
	v_add_f32_e32 v82, v90, v82
	v_add_f32_e32 v82, v91, v82
	v_add_f32_e32 v82, v92, v82
	v_add_f32_e32 v82, v93, v82
	v_add_f32_e32 v82, v94, v82
	v_add_f32_e32 v82, v95, v82
	v_add_f32_e32 v82, v96, v82
	v_add_f32_e32 v82, v97, v82
	v_add3_u32 v204, s13, v193, v194
	v_add_f32_e32 v197, v197, v82
	ds_read_b128 v[198:201], v204 offset:8704
	ds_read_b128 v[82:85], v204
	ds_read_b128 v[206:209], v204 offset:32
	s_waitcnt lgkmcnt(1)
	v_mfma_f32_32x32x16_bf16 v[98:113], v[82:85], v[114:117], v[66:81]
	v_mfma_f32_32x32x16_bf16 v[82:97], v[198:201], v[114:117], v[66:81]
	ds_read_b128 v[198:201], v204 offset:8736
	s_waitcnt lgkmcnt(1)
	v_mfma_f32_32x32x16_bf16 v[98:113], v[206:209], v[118:121], v[98:113]
	s_waitcnt lgkmcnt(0)
	v_mfma_f32_32x32x16_bf16 v[82:97], v[198:201], v[118:121], v[82:97]
	ds_read_b128 v[198:201], v204 offset:8768
	ds_read_b128 v[206:209], v204 offset:64
	s_waitcnt lgkmcnt(0)
	v_mfma_f32_32x32x16_bf16 v[98:113], v[206:209], v[122:125], v[98:113]
	v_mfma_f32_32x32x16_bf16 v[82:97], v[198:201], v[122:125], v[82:97]
	ds_read_b128 v[198:201], v204 offset:8800
	ds_read_b128 v[206:209], v204 offset:96
	s_waitcnt lgkmcnt(0)
	v_mfma_f32_32x32x16_bf16 v[98:113], v[206:209], v[126:129], v[98:113]
	v_mfma_f32_32x32x16_bf16 v[82:97], v[198:201], v[126:129], v[82:97]
	v_add_u32_e32 v198, s13, v195
	v_add3_u32 v204, v198, v0, s90
	ds_read_b64_tr_b16 v[198:199], v204 offset:0
	ds_read_b64_tr_b16 v[200:201], v204 offset:2560
	ds_read_b64_tr_b16 v[206:207], v204 offset:64
	ds_read_b64_tr_b16 v[208:209], v204 offset:2624
	ds_read_b64_tr_b16 v[210:211], v204 offset:128
	ds_read_b64_tr_b16 v[212:213], v204 offset:2688
	ds_read_b64_tr_b16 v[214:215], v204 offset:192
	ds_read_b64_tr_b16 v[216:217], v204 offset:2752
	s_nop 1
	v_max3_f32 v218, v98, v99, v82
	v_max3_f32 v219, v100, v101, v83
	v_max3_f32 v218, v218, v84, v85
	v_max3_f32 v219, v219, v104, v105
	v_max3_f32 v218, v218, v102, v103
	v_max3_f32 v219, v219, v88, v89
	v_max3_f32 v218, v218, v86, v87
	v_max3_f32 v219, v219, v108, v109
	v_max3_f32 v218, v218, v106, v107
	v_max3_f32 v219, v219, v92, v93
	v_max3_f32 v218, v218, v90, v91
	v_max3_f32 v219, v219, v112, v113
	v_max3_f32 v218, v218, v110, v111
	v_max3_f32 v219, v219, v96, v97
	v_max3_f32 v218, v218, v94, v95
	v_max3_f32 v218, v218, v219, v219
	v_mov_b32_e32 v219, v218
	s_nop 1
	v_permlane32_swap_b32_e32 v218, v219
	v_max_f32_e32 v219, v219, v219
	v_max_f32_e32 v218, v218, v218
	v_max_f32_e32 v218, v218, v219
	v_cmp_lt_f32_e32 vcc, s80, v218
	s_cbranch_vccz .LBB0_604
; template <int KW, int DV, bool NA> ...
;     ...
;         if (first || __any(mx > 6.f)) {
;             const float dl = first ? mx : fmaxf(mx, 0.f);
;             const float f = first ? 0.f : __builtin_amdgcn_exp2f(-dl);
;             m_ref += dl; l_run *= f;
; #pragma unroll
;             for (int r = 0; r < 16; ++r) negm[r] = -m_ref;
;             asm volatile("" : "+v"(negm));
; #pragma unroll
;             for (int r = 0; r < 16; ++r) { p0[r] -= dl; p1[r] -= dl; }
; #pragma unroll
;             for (int d = 0; d < DT; ++d)
; #pragma unroll
;                 for (int r = 0; r < 16; ++r) o[d][r] *= f;
;             first = false;
;         }
	v_max_f32_e32 v66, v218, v218
	v_max_f32_e32 v218, 0, v66
	v_exp_f32_e64 v220, -v218
	v_add_f32_e32 v196, v196, v218
	v_xor_b32_e32 v66, 0x80000000, v196
	v_mov_b32_e32 v67, v66
	v_mul_f32_e32 v197, v197, v220
	v_mov_b32_e32 v68, v66
	v_mov_b32_e32 v69, v66
	v_mov_b32_e32 v70, v66
	v_mov_b32_e32 v71, v66
	v_mov_b32_e32 v72, v66
	v_mov_b32_e32 v73, v66
	v_mov_b32_e32 v74, v66
	v_mov_b32_e32 v75, v66
	v_mov_b32_e32 v76, v66
	v_mov_b32_e32 v77, v66
	v_mov_b32_e32 v78, v66
	v_mov_b32_e32 v79, v66
	v_mov_b32_e32 v80, v66
	v_mov_b32_e32 v81, v66
	v_pk_add_f32 v[98:99], v[98:99], v[218:219] op_sel_hi:[1,0] neg_lo:[0,1] neg_hi:[0,1]
	v_pk_add_f32 v[82:83], v[82:83], v[218:219] op_sel_hi:[1,0] neg_lo:[0,1] neg_hi:[0,1]
	v_pk_add_f32 v[100:101], v[100:101], v[218:219] op_sel_hi:[1,0] neg_lo:[0,1] neg_hi:[0,1]
	v_pk_add_f32 v[84:85], v[84:85], v[218:219] op_sel_hi:[1,0] neg_lo:[0,1] neg_hi:[0,1]
	v_pk_add_f32 v[102:103], v[102:103], v[218:219] op_sel_hi:[1,0] neg_lo:[0,1] neg_hi:[0,1]
	v_pk_add_f32 v[86:87], v[86:87], v[218:219] op_sel_hi:[1,0] neg_lo:[0,1] neg_hi:[0,1]
	v_pk_add_f32 v[104:105], v[104:105], v[218:219] op_sel_hi:[1,0] neg_lo:[0,1] neg_hi:[0,1]
	v_pk_add_f32 v[88:89], v[88:89], v[218:219] op_sel_hi:[1,0] neg_lo:[0,1] neg_hi:[0,1]
	v_pk_add_f32 v[106:107], v[106:107], v[218:219] op_sel_hi:[1,0] neg_lo:[0,1] neg_hi:[0,1]
	v_pk_add_f32 v[90:91], v[90:91], v[218:219] op_sel_hi:[1,0] neg_lo:[0,1] neg_hi:[0,1]
	v_pk_add_f32 v[108:109], v[108:109], v[218:219] op_sel_hi:[1,0] neg_lo:[0,1] neg_hi:[0,1]
	v_pk_add_f32 v[92:93], v[92:93], v[218:219] op_sel_hi:[1,0] neg_lo:[0,1] neg_hi:[0,1]
	v_pk_add_f32 v[110:111], v[110:111], v[218:219] op_sel_hi:[1,0] neg_lo:[0,1] neg_hi:[0,1]
	v_pk_add_f32 v[94:95], v[94:95], v[218:219] op_sel_hi:[1,0] neg_lo:[0,1] neg_hi:[0,1]
	v_pk_add_f32 v[112:113], v[112:113], v[218:219] op_sel_hi:[1,0] neg_lo:[0,1] neg_hi:[0,1]
	v_pk_add_f32 v[96:97], v[96:97], v[218:219] op_sel_hi:[1,0] neg_lo:[0,1] neg_hi:[0,1]
	v_pk_mul_f32 v[64:65], v[64:65], v[220:221] op_sel_hi:[1,0]
	v_pk_mul_f32 v[62:63], v[62:63], v[220:221] op_sel_hi:[1,0]
	v_pk_mul_f32 v[60:61], v[60:61], v[220:221] op_sel_hi:[1,0]
	v_pk_mul_f32 v[58:59], v[58:59], v[220:221] op_sel_hi:[1,0]
	v_pk_mul_f32 v[56:57], v[56:57], v[220:221] op_sel_hi:[1,0]
	v_pk_mul_f32 v[54:55], v[54:55], v[220:221] op_sel_hi:[1,0]
	v_pk_mul_f32 v[52:53], v[52:53], v[220:221] op_sel_hi:[1,0]
	v_pk_mul_f32 v[50:51], v[50:51], v[220:221] op_sel_hi:[1,0]
	v_pk_mul_f32 v[48:49], v[48:49], v[220:221] op_sel_hi:[1,0]
	v_pk_mul_f32 v[46:47], v[46:47], v[220:221] op_sel_hi:[1,0]
	v_pk_mul_f32 v[44:45], v[44:45], v[220:221] op_sel_hi:[1,0]
	v_pk_mul_f32 v[42:43], v[42:43], v[220:221] op_sel_hi:[1,0]
	v_pk_mul_f32 v[40:41], v[40:41], v[220:221] op_sel_hi:[1,0]
	v_pk_mul_f32 v[38:39], v[38:39], v[220:221] op_sel_hi:[1,0]
	v_pk_mul_f32 v[36:37], v[36:37], v[220:221] op_sel_hi:[1,0]
	v_pk_mul_f32 v[34:35], v[34:35], v[220:221] op_sel_hi:[1,0]
	v_pk_mul_f32 v[32:33], v[32:33], v[220:221] op_sel_hi:[1,0]
	v_pk_mul_f32 v[30:31], v[30:31], v[220:221] op_sel_hi:[1,0]
	v_pk_mul_f32 v[28:29], v[28:29], v[220:221] op_sel_hi:[1,0]
	v_pk_mul_f32 v[26:27], v[26:27], v[220:221] op_sel_hi:[1,0]
	v_pk_mul_f32 v[24:25], v[24:25], v[220:221] op_sel_hi:[1,0]
	v_pk_mul_f32 v[22:23], v[22:23], v[220:221] op_sel_hi:[1,0]
	v_pk_mul_f32 v[20:21], v[20:21], v[220:221] op_sel_hi:[1,0]
	v_pk_mul_f32 v[18:19], v[18:19], v[220:221] op_sel_hi:[1,0]
	v_pk_mul_f32 v[16:17], v[16:17], v[220:221] op_sel_hi:[1,0]
	v_pk_mul_f32 v[14:15], v[14:15], v[220:221] op_sel_hi:[1,0]
	v_pk_mul_f32 v[12:13], v[12:13], v[220:221] op_sel_hi:[1,0]
	v_pk_mul_f32 v[10:11], v[10:11], v[220:221] op_sel_hi:[1,0]
	v_pk_mul_f32 v[8:9], v[8:9], v[220:221] op_sel_hi:[1,0]
	v_pk_mul_f32 v[6:7], v[6:7], v[220:221] op_sel_hi:[1,0]
	v_pk_mul_f32 v[4:5], v[4:5], v[220:221] op_sel_hi:[1,0]
	v_pk_mul_f32 v[2:3], v[2:3], v[220:221] op_sel_hi:[1,0]
; #define TR_ISSUE(KS, d) do { \
;             asm volatile("ds_read_b64_tr_b16 %0, %1 offset:%c2" : "=&v"(lo[d]) : "v"(vb), "i"((16 * (KS)) * VSTR + 64 * (d)) : "memory"); \
;             asm volatile("ds_read_b64_tr_b16 %0, %1 offset:%c2" : "=&v"(hh[d]) : "v"(vb), "i"((16 * (KS) + 8) * VSTR + 64 * (d)) : "memory"); } while (0)
; #define SM_SLICE(P, LO, HI) _Pragma("unroll") for (int r = (LO); r < (HI); ++r) { P[r] = __builtin_amdgcn_exp2f(P[r]); ps += P[r]; }
; #define PACK8(P, B) ((u32x4){pk2(P[(B)], P[(B) + 1]), pk2(P[(B) + 2], P[(B) + 3]), pk2(P[(B) + 4], P[(B) + 5]), pk2(P[(B) + 6], P[(B) + 7])})
; template <int KW, int DV, bool NA> ...
;     ...
; #pragma unroll
;         for (int d = 0; d < DT; ++d) TR_ISSUE(0, d);
;         float ps = 0.f;
;         SM_SLICE(p0, 0, 8); pw[0] = PACK8(p0, 0);
; #pragma unroll
;         for (int d = 0; d < DT; ++d) {
;             LGKM_WAIT(2 * (DT - 1));
;             o[d] = __builtin_amdgcn_mfma_f32_32x32x16_bf16(PV_VF(d), __builtin_bit_cast(bf16x8, pw[0]), o[d], 0, 0, 0);
;             TR_ISSUE(1, d);
;             SM_SLICE(p0, 8 + d * (8 / DT), 8 + (d + 1) * (8 / DT));
;             __builtin_amdgcn_sched_barrier(0);
;         }
;         pw[1] = PACK8(p0, 8);
; #pragma unroll
;         for (int d = 0; d < DT; ++d) {
;             LGKM_WAIT(2 * (DT - 1));
;             o[d] = __builtin_amdgcn_mfma_f32_32x32x16_bf16(PV_VF(d), __builtin_bit_cast(bf16x8, pw[1]), o[d], 0, 0, 0);
;             TR_ISSUE(2, d);
;             SM_SLICE(p1, d * (8 / DT), (d + 1) * (8 / DT));
;             __builtin_amdgcn_sched_barrier(0);
;         }
;         pw[2] = PACK8(p1, 0);
; #pragma unroll
;         for (int d = 0; d < DT; ++d) {
;             LGKM_WAIT(2 * (DT - 1));
;             o[d] = __builtin_amdgcn_mfma_f32_32x32x16_bf16(PV_VF(d), __builtin_bit_cast(bf16x8, pw[2]), o[d], 0, 0, 0);
;             TR_ISSUE(3, d);
;             SM_SLICE(p1, 8 + d * (8 / DT), 8 + (d + 1) * (8 / DT));
;             __builtin_amdgcn_sched_barrier(0);
;         }
;         pw[3] = PACK8(p1, 8);
;         l_run += ps;
;         asm volatile("s_waitcnt lgkmcnt(0)" ::: "memory"); __builtin_amdgcn_sched_barrier(0);
; #pragma unroll
;         for (int d = 0; d < DT; ++d) o[d] = __builtin_amdgcn_mfma_f32_32x32x16_bf16(PV_VF(d), __builtin_bit_cast(bf16x8, pw[3]), o[d], 0, 0, 0);
.LBB0_604:
	v_exp_f32_e32 v218, v98
	v_exp_f32_e32 v219, v99
	v_exp_f32_e32 v220, v100
	v_exp_f32_e32 v221, v101
	v_exp_f32_e32 v222, v102
	v_exp_f32_e32 v223, v103
	v_exp_f32_e32 v224, v104
	v_exp_f32_e32 v225, v105
	s_waitcnt lgkmcnt(6)
	v_cvt_pk_bf16_f32 v98, v218, v219
	v_cvt_pk_bf16_f32 v99, v220, v221
	v_cvt_pk_bf16_f32 v100, v222, v223
	v_cvt_pk_bf16_f32 v101, v224, v225
	s_nop 1
	v_mfma_f32_32x32x16_bf16 v[50:65], v[198:201], v[98:101], v[50:65]
	ds_read_b64_tr_b16 v[102:103], v204 offset:5120
	ds_read_b64_tr_b16 v[104:105], v204 offset:7680
	v_exp_f32_e32 v226, v106
	v_exp_f32_e32 v227, v107
	s_waitcnt lgkmcnt(6)
	v_mfma_f32_32x32x16_bf16 v[34:49], v[206:209], v[98:101], v[34:49]
	ds_read_b64_tr_b16 v[198:199], v204 offset:5184
	ds_read_b64_tr_b16 v[200:201], v204 offset:7744
	v_exp_f32_e32 v206, v108
	v_exp_f32_e32 v207, v109
	s_waitcnt lgkmcnt(6)
	v_mfma_f32_32x32x16_bf16 v[18:33], v[210:213], v[98:101], v[18:33]
	ds_read_b64_tr_b16 v[106:107], v204 offset:5248
	ds_read_b64_tr_b16 v[108:109], v204 offset:7808
	v_exp_f32_e32 v208, v110
	v_exp_f32_e32 v209, v111
	s_waitcnt lgkmcnt(6)
	v_mfma_f32_32x32x16_bf16 v[2:17], v[214:217], v[98:101], v[2:17]
	ds_read_b64_tr_b16 v[98:99], v204 offset:5312
	ds_read_b64_tr_b16 v[100:101], v204 offset:7872
	v_exp_f32_e32 v210, v112
	v_exp_f32_e32 v211, v113
	s_waitcnt lgkmcnt(6)
	v_cvt_pk_bf16_f32 v110, v226, v227
	v_cvt_pk_bf16_f32 v111, v206, v207
	v_cvt_pk_bf16_f32 v112, v208, v209
	v_cvt_pk_bf16_f32 v113, v210, v211
	s_nop 1
	v_mfma_f32_32x32x16_bf16 v[50:65], v[102:105], v[110:113], v[50:65]
	ds_read_b64_tr_b16 v[102:103], v204 offset:10240
	ds_read_b64_tr_b16 v[104:105], v204 offset:12800
	v_exp_f32_e32 v212, v82
	v_exp_f32_e32 v213, v83
	s_waitcnt lgkmcnt(6)
	v_mfma_f32_32x32x16_bf16 v[34:49], v[198:201], v[110:113], v[34:49]
	ds_read_b64_tr_b16 v[198:199], v204 offset:10304
	ds_read_b64_tr_b16 v[200:201], v204 offset:12864
	v_exp_f32_e32 v214, v84
	v_exp_f32_e32 v215, v85
	s_waitcnt lgkmcnt(6)
	v_mfma_f32_32x32x16_bf16 v[18:33], v[106:109], v[110:113], v[18:33]
	ds_read_b64_tr_b16 v[82:83], v204 offset:10368
	ds_read_b64_tr_b16 v[84:85], v204 offset:12928
	v_exp_f32_e32 v216, v86
	v_exp_f32_e32 v217, v87
	s_waitcnt lgkmcnt(6)
	v_mfma_f32_32x32x16_bf16 v[2:17], v[98:101], v[110:113], v[2:17]
	ds_read_b64_tr_b16 v[98:99], v204 offset:10432
	ds_read_b64_tr_b16 v[100:101], v204 offset:12992
	v_exp_f32_e32 v110, v88
	v_exp_f32_e32 v111, v89
	s_waitcnt lgkmcnt(6)
	v_cvt_pk_bf16_f32 v86, v212, v213
	v_cvt_pk_bf16_f32 v87, v214, v215
	v_cvt_pk_bf16_f32 v88, v216, v217
	v_cvt_pk_bf16_f32 v89, v110, v111
	s_nop 1
	v_mfma_f32_32x32x16_bf16 v[50:65], v[102:105], v[86:89], v[50:65]
	ds_read_b64_tr_b16 v[102:103], v204 offset:15360
	ds_read_b64_tr_b16 v[104:105], v204 offset:17920
	s_waitcnt lgkmcnt(6)
	v_mfma_f32_32x32x16_bf16 v[34:49], v[198:201], v[86:89], v[34:49]
	ds_read_b64_tr_b16 v[106:107], v204 offset:15424
	ds_read_b64_tr_b16 v[108:109], v204 offset:17984
	s_waitcnt lgkmcnt(6)
	v_mfma_f32_32x32x16_bf16 v[18:33], v[82:85], v[86:89], v[18:33]
	ds_read_b64_tr_b16 v[82:83], v204 offset:15488
	ds_read_b64_tr_b16 v[84:85], v204 offset:18048
	s_waitcnt lgkmcnt(6)
	v_mfma_f32_32x32x16_bf16 v[2:17], v[98:101], v[86:89], v[2:17]
	v_add_f32_e32 v98, 0, v218
	v_add_f32_e32 v98, v219, v98
	v_add_f32_e32 v98, v220, v98
	v_add_f32_e32 v98, v221, v98
	v_add_f32_e32 v98, v222, v98
	v_add_f32_e32 v98, v223, v98
	v_add_f32_e32 v98, v224, v98
	v_add_f32_e32 v98, v225, v98
	v_add_f32_e32 v98, v226, v98
	v_add_f32_e32 v98, v227, v98
	v_add_f32_e32 v98, v206, v98
	v_add_f32_e32 v98, v207, v98
	v_add_f32_e32 v98, v208, v98
	v_add_f32_e32 v98, v209, v98
	v_add_f32_e32 v98, v210, v98
	v_add_f32_e32 v98, v211, v98
	v_add_f32_e32 v98, v212, v98
	v_add_f32_e32 v98, v213, v98
	v_add_f32_e32 v98, v214, v98
	v_add_f32_e32 v98, v215, v98
	v_add_f32_e32 v98, v216, v98
	v_exp_f32_e32 v90, v90
	v_add_f32_e32 v98, v217, v98
	v_exp_f32_e32 v91, v91
	v_add_f32_e32 v98, v110, v98
	v_exp_f32_e32 v92, v92
	v_add_f32_e32 v98, v111, v98
	v_exp_f32_e32 v93, v93
	v_add_f32_e32 v98, v90, v98
	v_exp_f32_e32 v94, v94
	v_add_f32_e32 v98, v91, v98
	v_exp_f32_e32 v95, v95
	v_add_f32_e32 v98, v92, v98
	v_exp_f32_e32 v96, v96
	ds_read_b64_tr_b16 v[86:87], v204 offset:15552
	v_add_f32_e32 v98, v93, v98
	v_exp_f32_e32 v97, v97
	ds_read_b64_tr_b16 v[88:89], v204 offset:18112
	v_add_f32_e32 v98, v94, v98
	v_add_f32_e32 v98, v95, v98
	v_add_f32_e32 v98, v96, v98
	v_add_f32_e32 v98, v97, v98
	s_waitcnt lgkmcnt(0)
	v_add_f32_e32 v197, v197, v98
	v_cvt_pk_bf16_f32 v90, v90, v91
	v_cvt_pk_bf16_f32 v91, v92, v93
	v_cvt_pk_bf16_f32 v92, v94, v95
	v_cvt_pk_bf16_f32 v93, v96, v97
	s_nop 1
	v_mfma_f32_32x32x16_bf16 v[50:65], v[102:105], v[90:93], v[50:65]
	s_add_i32 s8, s8, 2
	s_mov_b64 s[0:1], 0
	s_cmpk_lt_u32 s12, 0x42
	s_barrier
	v_mfma_f32_32x32x16_bf16 v[34:49], v[106:109], v[90:93], v[34:49]
	v_mfma_f32_32x32x16_bf16 v[18:33], v[82:85], v[90:93], v[18:33]
	v_mfma_f32_32x32x16_bf16 v[2:17], v[86:89], v[90:93], v[2:17]
	s_cbranch_scc0 .LBB0_606
	s_mov_b32 s2, s10
	s_mov_b32 s10, s9
	s_mov_b32 s9, s11
	s_branch .LBB0_591
